# work queues: a block gives up after 2 queue visits instead of 8 (shorter end-of-phase tail of failing pops), all four queue-driven phases
# speedup vs baseline: 1.0232x; 1.0157x over previous
.LBB0_198:
	s_or_b64 exec, exec, s[4:5]
	s_waitcnt lgkmcnt(0)
	s_barrier
	ds_read_b32 v0, v103
	s_movk_i32 s4, 0x1b0
	s_waitcnt lgkmcnt(0)
	v_cmp_gt_i32_e32 vcc, s4, v0
	v_readfirstlane_b32 s6, v0
	s_mov_b64 s[4:5], 0
	s_cbranch_vccnz .LBB0_201
	s_cmp_gt_i32 s47, 0
	s_cbranch_scc1 .LBB0_202
	s_add_i32 s4, s37, 1
	s_and_b32 s37, s4, 7
	s_add_i32 s47, s47, 1
	s_cbranch_execnz .LBB0_194
	s_branch .LBB0_203

.LBB0_610:
	s_or_b64 exec, exec, s[28:29]
	s_waitcnt lgkmcnt(0)
	s_barrier
	ds_read_b32 v0, v220
	s_movk_i32 s28, 0x120
	s_waitcnt lgkmcnt(0)
	v_cmp_gt_i32_e32 vcc, s28, v0
	v_readfirstlane_b32 s30, v0
	s_mov_b64 s[28:29], 0
	s_cbranch_vccnz .LBB0_613
	s_cmp_gt_i32 s63, 0
	s_cbranch_scc1 .LBB0_614
	s_add_i32 s28, s52, 1
	s_and_b32 s52, s28, 7
	s_add_i32 s63, s63, 1
	s_cbranch_execnz .LBB0_606
	s_branch .LBB0_615

.LBB0_814:
	s_or_b64 exec, exec, s[2:3]
	s_waitcnt lgkmcnt(0)
	s_barrier
	ds_read_b32 v0, v178
	s_movk_i32 s2, 0x100
	s_waitcnt lgkmcnt(0)
	v_cmp_gt_i32_e32 vcc, s2, v0
	v_readfirstlane_b32 s33, v0
	s_mov_b64 s[2:3], 0
	s_cbranch_vccnz .LBB0_817
	v_readlane_b32 s33, v248, 10
	s_cmp_gt_i32 s33, 0
	s_cbranch_scc1 .LBB0_818
	v_readlane_b32 s2, v248, 8
	s_add_i32 s2, s2, 1
	s_and_b32 s2, s2, 7
	v_writelane_b32 v248, s2, 8
	s_mov_b64 s[2:3], -1
	s_branch .LBB0_819

.LBB0_896:
	s_or_b64 exec, exec, s[8:9]
	s_waitcnt lgkmcnt(0)
	s_barrier
	ds_read_b32 v0, v105
	s_mov_b64 s[8:9], 0
	s_waitcnt lgkmcnt(0)
	v_cmp_gt_i32_e32 vcc, s15, v0
	v_readfirstlane_b32 s0, v0
	s_cbranch_vccnz .LBB0_899
	s_cmp_gt_i32 s20, 0
	s_cbranch_scc1 .LBB0_900
	s_add_i32 s0, s14, 1
	s_and_b32 s14, s0, 7
	s_add_i32 s20, s20, 1
	s_cbranch_execnz .LBB0_892
	s_branch .LBB0_901
